# finish units remapped to the XCD that owns their rows; post-finish barrier XCD-local; per-XCD carry stores only the entries its own finish units read
# baseline (speedup 1.0000x reference)
; __device__ __forceinline__ void carry_phase(const Args& a, int bx) {
;     int tid_ = threadIdx.x; asm volatile("" : "+v"(tid_));
;     const int gt = bx * NTHR + tid_;
;     if (gt >= NB * 2 * LW) return;
;     const int b = gt >> 10, dir = (gt >> 9) & 1, c = gt & 511;
;     const f32x2* tot = (const f32x2*)(a.ws + WS_TOT); float* car = (float*)(a.ws + WS_CAR);
;     float hc = 0.f;
; #pragma unroll 1
;     for (int j0 = 0; j0 < NCH; j0 += 32) {
;         f32x2 v[32];
; #pragma unroll
;         for (int i = 0; i < 32; ++i) { const int j = j0 + i, cj = dir == 0 ? j : NCH - 1 - j; v[i] = tot[(size_t)((b * NCH + cj) * 2 + dir) * LW + c]; }
; #pragma unroll
;         for (int i = 0; i < 32; ++i) { const int j = j0 + i, cj = dir == 0 ? j : NCH - 1 - j; car[(size_t)((b * NCH + cj) * 2 + dir) * LW + c] = hc; hc = v[i].x * hc + v[i].y; }
.LBB0_252:
	s_or_b64 exec, exec, s[0:1]
	s_waitcnt lgkmcnt(0)
	v_mov_b32_e32 v2, v226
	s_lshr_b32 s0, s2, 3
	s_lshl_b32 s0, s0, 9
	s_barrier
	s_nop 0
	v_add_u32_e32 v0, s0, v2
	s_movk_i32 s0, 0x1000
	v_cmp_gt_i32_e32 vcc, s0, v0
	s_and_saveexec_b64 s[0:1], vcc
	s_xor_b64 s[0:1], exec, s[0:1]
	s_cbranch_execz .LBB0_255
	v_mov_b32_e32 v5, 0x2000c
	ds_read_b32 v5, v5
	s_lshr_b32 s29, s2, 3
	s_and_b32 s28, s2, 7
	s_lshr_b32 s38, s29, 1
	s_lshr_b32 s39, s28, 1
	s_and_b32 s28, s28, 1
	s_and_b32 s29, s29, 1
	s_xor_b32 s28, s28, s29
	s_lshl_b32 s28, 1, s28
	s_cmp_eq_u32 s38, s39
	s_cselect_b32 s28, s28, 0
	s_waitcnt lgkmcnt(0)
	v_readfirstlane_b32 s29, v5
	s_cmp_eq_u32 s29, 0
	s_cbranch_scc1 .Lcar_m
	s_mov_b32 s28, 3

; __device__ __forceinline__ void carry_phase(const Args& a, int bx) {
;     ...
;         for (int i = 0; i < 32; ++i) { const int j = j0 + i, cj = dir == 0 ? j : NCH - 1 - j; v[i] = tot[(size_t)((b * NCH + cj) * 2 + dir) * LW + c]; }
; #pragma unroll
;         for (int i = 0; i < 32; ++i) { const int j = j0 + i, cj = dir == 0 ? j : NCH - 1 - j; car[(size_t)((b * NCH + cj) * 2 + dir) * LW + c] = hc; hc = v[i].x * hc + v[i].y; }
.Lcs_1:
	v_add_u32_e32 v7, v7, v10
	v_fma_f32 v13, v16, v13, v17
	s_bitcmp1_b32 s28, 0
	s_cbranch_scc0 .Lcs_2
	global_store_dword v7, v13, s[4:5]
.Lcs_2:
	v_add_u32_e32 v7, v7, v10
	v_fma_f32 v13, v18, v13, v19
	s_bitcmp1_b32 s28, 0
	s_cbranch_scc0 .Lcs_3
	global_store_dword v7, v13, s[4:5]
.Lcs_3:
	v_add_u32_e32 v7, v7, v10
	v_fma_f32 v13, v20, v13, v21
	s_bitcmp1_b32 s28, 0
	s_cbranch_scc0 .Lcs_4
	global_store_dword v7, v13, s[4:5]
.Lcs_4:
	v_add_u32_e32 v7, v7, v10
	v_fma_f32 v13, v22, v13, v23
	s_bitcmp1_b32 s28, 0
	s_cbranch_scc0 .Lcs_5
	global_store_dword v7, v13, s[4:5]
.Lcs_5:
	v_add_u32_e32 v7, v7, v10
	v_fma_f32 v13, v24, v13, v25
	s_bitcmp1_b32 s28, 0
	s_cbranch_scc0 .Lcs_6
	global_store_dword v7, v13, s[4:5]
.Lcs_6:
	v_add_u32_e32 v7, v7, v10
	v_fma_f32 v13, v26, v13, v27
	s_bitcmp1_b32 s28, 0
	s_cbranch_scc0 .Lcs_7
	global_store_dword v7, v13, s[4:5]
.Lcs_7:
	v_add_u32_e32 v7, v7, v10
	v_fma_f32 v13, v28, v13, v29
	s_bitcmp1_b32 s28, 0
	s_cbranch_scc0 .Lcs_8
	global_store_dword v7, v13, s[4:5]
.Lcs_8:
	v_add_u32_e32 v7, v7, v10
	v_fma_f32 v13, v30, v13, v31
	s_bitcmp1_b32 s28, 0
	s_cbranch_scc0 .Lcs_9
	global_store_dword v7, v13, s[4:5]
.Lcs_9:
	v_add_u32_e32 v7, v7, v10
	v_fma_f32 v13, v32, v13, v33
	s_bitcmp1_b32 s28, 0
	s_cbranch_scc0 .Lcs_10
	global_store_dword v7, v13, s[4:5]
.Lcs_10:
	v_add_u32_e32 v7, v7, v10
	v_fma_f32 v13, v34, v13, v35
	s_bitcmp1_b32 s28, 0
	s_cbranch_scc0 .Lcs_11
	global_store_dword v7, v13, s[4:5]
.Lcs_11:
	v_add_u32_e32 v7, v7, v10
	v_fma_f32 v13, v36, v13, v37
	s_bitcmp1_b32 s28, 0
	s_cbranch_scc0 .Lcs_12
	global_store_dword v7, v13, s[4:5]
.Lcs_12:
	v_add_u32_e32 v7, v7, v10
	v_fma_f32 v13, v38, v13, v39
	s_bitcmp1_b32 s28, 0
	s_cbranch_scc0 .Lcs_13
	global_store_dword v7, v13, s[4:5]
.Lcs_13:
	v_add_u32_e32 v7, v7, v10
	v_fma_f32 v13, v40, v13, v41
	s_bitcmp1_b32 s28, 0
	s_cbranch_scc0 .Lcs_14
	global_store_dword v7, v13, s[4:5]
.Lcs_14:
	v_add_u32_e32 v7, v7, v10
	v_fma_f32 v13, v42, v13, v43
	s_bitcmp1_b32 s28, 0
	s_cbranch_scc0 .Lcs_15
	global_store_dword v7, v13, s[4:5]

; __device__ __forceinline__ void carry_phase(const Args& a, int bx) {
;     ...
;         for (int i = 0; i < 32; ++i) { const int j = j0 + i, cj = dir == 0 ? j : NCH - 1 - j; v[i] = tot[(size_t)((b * NCH + cj) * 2 + dir) * LW + c]; }
; #pragma unroll
;         for (int i = 0; i < 32; ++i) { const int j = j0 + i, cj = dir == 0 ? j : NCH - 1 - j; car[(size_t)((b * NCH + cj) * 2 + dir) * LW + c] = hc; hc = v[i].x * hc + v[i].y; }
.Lcs_17:
	v_add_u32_e32 v7, v7, v10
	v_fma_f32 v13, v48, v13, v49
	s_bitcmp1_b32 s28, 0
	s_cbranch_scc0 .Lcs_18
	global_store_dword v7, v13, s[4:5]
.Lcs_18:
	v_add_u32_e32 v7, v7, v10
	v_fma_f32 v13, v50, v13, v51
	s_bitcmp1_b32 s28, 0
	s_cbranch_scc0 .Lcs_19
	global_store_dword v7, v13, s[4:5]
.Lcs_19:
	v_add_u32_e32 v7, v7, v10
	v_fma_f32 v13, v52, v13, v53
	s_bitcmp1_b32 s28, 0
	s_cbranch_scc0 .Lcs_20
	global_store_dword v7, v13, s[4:5]
.Lcs_20:
	v_add_u32_e32 v7, v7, v10
	v_fma_f32 v13, v54, v13, v55
	s_bitcmp1_b32 s28, 0
	s_cbranch_scc0 .Lcs_21
	global_store_dword v7, v13, s[4:5]
.Lcs_21:
	v_add_u32_e32 v7, v7, v10
	v_fma_f32 v13, v56, v13, v57
	s_bitcmp1_b32 s28, 0
	s_cbranch_scc0 .Lcs_22
	global_store_dword v7, v13, s[4:5]
.Lcs_22:
	v_add_u32_e32 v7, v7, v10
	v_fma_f32 v13, v58, v13, v59
	s_bitcmp1_b32 s28, 0
	s_cbranch_scc0 .Lcs_23
	global_store_dword v7, v13, s[4:5]
.Lcs_23:
	v_add_u32_e32 v7, v7, v10
	v_fma_f32 v13, v60, v13, v61
	s_bitcmp1_b32 s28, 0
	s_cbranch_scc0 .Lcs_24
	global_store_dword v7, v13, s[4:5]
.Lcs_24:
	v_add_u32_e32 v7, v7, v10
	v_fma_f32 v13, v62, v13, v63
	s_bitcmp1_b32 s28, 0
	s_cbranch_scc0 .Lcs_25
	global_store_dword v7, v13, s[4:5]
.Lcs_25:
	v_add_u32_e32 v7, v7, v10
	v_fma_f32 v13, v64, v13, v65
	s_bitcmp1_b32 s28, 0
	s_cbranch_scc0 .Lcs_26
	global_store_dword v7, v13, s[4:5]
.Lcs_26:
	v_add_u32_e32 v7, v7, v10
	v_fma_f32 v13, v66, v13, v67
	s_bitcmp1_b32 s28, 0
	s_cbranch_scc0 .Lcs_27
	global_store_dword v7, v13, s[4:5]
.Lcs_27:
	v_add_u32_e32 v7, v7, v10
	v_fma_f32 v13, v68, v13, v69
	s_bitcmp1_b32 s28, 0
	s_cbranch_scc0 .Lcs_28
	global_store_dword v7, v13, s[4:5]
.Lcs_28:
	v_add_u32_e32 v7, v7, v10
	v_fma_f32 v13, v70, v13, v71
	s_bitcmp1_b32 s28, 0
	s_cbranch_scc0 .Lcs_29
	global_store_dword v7, v13, s[4:5]
.Lcs_29:
	v_add_u32_e32 v7, v7, v10
	v_fma_f32 v13, v72, v13, v73
	s_bitcmp1_b32 s28, 0
	s_cbranch_scc0 .Lcs_30
	global_store_dword v7, v13, s[4:5]
.Lcs_30:
	v_add_u32_e32 v7, v7, v10
	v_fma_f32 v13, v74, v13, v75
	s_bitcmp1_b32 s28, 0
	s_cbranch_scc0 .Lcs_31
	global_store_dword v7, v13, s[4:5]

; __device__ __forceinline__ void carry_phase(const Args& a, int bx) {
;     ...
;         for (int i = 0; i < 32; ++i) { const int j = j0 + i, cj = dir == 0 ? j : NCH - 1 - j; v[i] = tot[(size_t)((b * NCH + cj) * 2 + dir) * LW + c]; }
; #pragma unroll
;         for (int i = 0; i < 32; ++i) { const int j = j0 + i, cj = dir == 0 ? j : NCH - 1 - j; car[(size_t)((b * NCH + cj) * 2 + dir) * LW + c] = hc; hc = v[i].x * hc + v[i].y; }
.Lcs_33:
	v_add_u32_e32 v7, v7, v10
	v_fma_f32 v13, v80, v13, v81
	s_bitcmp1_b32 s28, 0
	s_cbranch_scc0 .Lcs_34
	global_store_dword v7, v13, s[4:5]
.Lcs_34:
	v_add_u32_e32 v7, v7, v10
	v_fma_f32 v13, v82, v13, v83
	s_bitcmp1_b32 s28, 0
	s_cbranch_scc0 .Lcs_35
	global_store_dword v7, v13, s[4:5]
.Lcs_35:
	v_add_u32_e32 v7, v7, v10
	v_fma_f32 v13, v84, v13, v85
	s_bitcmp1_b32 s28, 0
	s_cbranch_scc0 .Lcs_36
	global_store_dword v7, v13, s[4:5]
.Lcs_36:
	v_add_u32_e32 v7, v7, v10
	v_fma_f32 v13, v86, v13, v87
	s_bitcmp1_b32 s28, 0
	s_cbranch_scc0 .Lcs_37
	global_store_dword v7, v13, s[4:5]
.Lcs_37:
	v_add_u32_e32 v7, v7, v10
	v_fma_f32 v13, v88, v13, v89
	s_bitcmp1_b32 s28, 0
	s_cbranch_scc0 .Lcs_38
	global_store_dword v7, v13, s[4:5]
.Lcs_38:
	v_add_u32_e32 v7, v7, v10
	v_fma_f32 v13, v90, v13, v91
	s_bitcmp1_b32 s28, 0
	s_cbranch_scc0 .Lcs_39
	global_store_dword v7, v13, s[4:5]
.Lcs_39:
	v_add_u32_e32 v7, v7, v10
	v_fma_f32 v13, v92, v13, v93
	s_bitcmp1_b32 s28, 0
	s_cbranch_scc0 .Lcs_40
	global_store_dword v7, v13, s[4:5]
.Lcs_40:
	v_add_u32_e32 v7, v7, v10
	v_fma_f32 v13, v94, v13, v95
	s_bitcmp1_b32 s28, 0
	s_cbranch_scc0 .Lcs_41
	global_store_dword v7, v13, s[4:5]
.Lcs_41:
	v_add_u32_e32 v7, v7, v10
	v_fma_f32 v13, v96, v13, v97
	s_bitcmp1_b32 s28, 0
	s_cbranch_scc0 .Lcs_42
	global_store_dword v7, v13, s[4:5]
.Lcs_42:
	v_add_u32_e32 v7, v7, v10
	v_fma_f32 v13, v98, v13, v99
	s_bitcmp1_b32 s28, 0
	s_cbranch_scc0 .Lcs_43
	global_store_dword v7, v13, s[4:5]
.Lcs_43:
	v_add_u32_e32 v7, v7, v10
	v_fma_f32 v13, v100, v13, v101
	s_bitcmp1_b32 s28, 0
	s_cbranch_scc0 .Lcs_44
	global_store_dword v7, v13, s[4:5]
.Lcs_44:
	v_add_u32_e32 v7, v7, v10
	v_fma_f32 v13, v102, v13, v103
	s_bitcmp1_b32 s28, 0
	s_cbranch_scc0 .Lcs_45
	global_store_dword v7, v13, s[4:5]
.Lcs_45:
	v_add_u32_e32 v7, v7, v10
	v_fma_f32 v13, v104, v13, v105
	s_bitcmp1_b32 s28, 0
	s_cbranch_scc0 .Lcs_46
	global_store_dword v7, v13, s[4:5]
.Lcs_46:
	v_add_u32_e32 v7, v7, v10
	v_fma_f32 v13, v106, v13, v107
	s_bitcmp1_b32 s28, 0
	s_cbranch_scc0 .Lcs_47
	global_store_dword v7, v13, s[4:5]

; __device__ __forceinline__ void carry_phase(const Args& a, int bx) {
;     ...
;         for (int i = 0; i < 32; ++i) { const int j = j0 + i, cj = dir == 0 ? j : NCH - 1 - j; v[i] = tot[(size_t)((b * NCH + cj) * 2 + dir) * LW + c]; }
; #pragma unroll
;         for (int i = 0; i < 32; ++i) { const int j = j0 + i, cj = dir == 0 ? j : NCH - 1 - j; car[(size_t)((b * NCH + cj) * 2 + dir) * LW + c] = hc; hc = v[i].x * hc + v[i].y; }
.Lcs_49:
	v_add_u32_e32 v7, v7, v10
	v_fma_f32 v13, v112, v13, v113
	s_bitcmp1_b32 s28, 0
	s_cbranch_scc0 .Lcs_50
	global_store_dword v7, v13, s[4:5]
.Lcs_50:
	v_add_u32_e32 v7, v7, v10
	v_fma_f32 v13, v114, v13, v115
	s_bitcmp1_b32 s28, 0
	s_cbranch_scc0 .Lcs_51
	global_store_dword v7, v13, s[4:5]
.Lcs_51:
	v_add_u32_e32 v7, v7, v10
	v_fma_f32 v13, v116, v13, v117
	s_bitcmp1_b32 s28, 0
	s_cbranch_scc0 .Lcs_52
	global_store_dword v7, v13, s[4:5]
.Lcs_52:
	v_add_u32_e32 v7, v7, v10
	v_fma_f32 v13, v118, v13, v119
	s_bitcmp1_b32 s28, 0
	s_cbranch_scc0 .Lcs_53
	global_store_dword v7, v13, s[4:5]
.Lcs_53:
	v_add_u32_e32 v7, v7, v10
	v_fma_f32 v13, v120, v13, v121
	s_bitcmp1_b32 s28, 0
	s_cbranch_scc0 .Lcs_54
	global_store_dword v7, v13, s[4:5]
.Lcs_54:
	v_add_u32_e32 v7, v7, v10
	v_fma_f32 v13, v122, v13, v123
	s_bitcmp1_b32 s28, 0
	s_cbranch_scc0 .Lcs_55
	global_store_dword v7, v13, s[4:5]
.Lcs_55:
	v_add_u32_e32 v7, v7, v10
	v_fma_f32 v13, v124, v13, v125
	s_bitcmp1_b32 s28, 0
	s_cbranch_scc0 .Lcs_56
	global_store_dword v7, v13, s[4:5]
.Lcs_56:
	v_add_u32_e32 v7, v7, v10
	v_fma_f32 v13, v126, v13, v127
	s_bitcmp1_b32 s28, 0
	s_cbranch_scc0 .Lcs_57
	global_store_dword v7, v13, s[4:5]
.Lcs_57:
	v_add_u32_e32 v7, v7, v10
	v_fma_f32 v13, v128, v13, v129
	s_bitcmp1_b32 s28, 0
	s_cbranch_scc0 .Lcs_58
	global_store_dword v7, v13, s[4:5]
.Lcs_58:
	v_add_u32_e32 v7, v7, v10
	v_fma_f32 v13, v130, v13, v131
	s_bitcmp1_b32 s28, 0
	s_cbranch_scc0 .Lcs_59
	global_store_dword v7, v13, s[4:5]
.Lcs_59:
	v_add_u32_e32 v7, v7, v10
	v_fma_f32 v13, v132, v13, v133
	s_bitcmp1_b32 s28, 0
	s_cbranch_scc0 .Lcs_60
	global_store_dword v7, v13, s[4:5]
.Lcs_60:
	v_add_u32_e32 v7, v7, v10
	v_fma_f32 v13, v134, v13, v135
	s_bitcmp1_b32 s28, 0
	s_cbranch_scc0 .Lcs_61
	global_store_dword v7, v13, s[4:5]
.Lcs_61:
	v_add_u32_e32 v7, v7, v10
	v_fma_f32 v13, v136, v13, v137
	s_bitcmp1_b32 s28, 0
	s_cbranch_scc0 .Lcs_62
	global_store_dword v7, v13, s[4:5]
.Lcs_62:
	v_add_u32_e32 v7, v7, v10
	v_fma_f32 v13, v138, v13, v139
	s_bitcmp1_b32 s28, 0
	s_cbranch_scc0 .Lcs_63
	global_store_dword v7, v13, s[4:5]
.Lcs_63:
	v_add_u32_e32 v7, v7, v10
	v_fma_f32 v13, v140, v13, v141
	global_load_dwordx2 v[78:79], v6, s[74:75]
	v_add_u32_e32 v6, v6, v8
	global_load_dwordx2 v[80:81], v6, s[74:75]
	v_add_u32_e32 v6, v6, v8
	global_load_dwordx2 v[82:83], v6, s[74:75]
	v_add_u32_e32 v6, v6, v8
	global_load_dwordx2 v[84:85], v6, s[74:75]
	v_add_u32_e32 v6, v6, v8
	global_load_dwordx2 v[86:87], v6, s[74:75]
	v_add_u32_e32 v6, v6, v8
	global_load_dwordx2 v[88:89], v6, s[74:75]
	v_add_u32_e32 v6, v6, v8
	global_load_dwordx2 v[90:91], v6, s[74:75]
	v_add_u32_e32 v6, v6, v8
	global_load_dwordx2 v[92:93], v6, s[74:75]
	v_add_u32_e32 v6, v6, v8
	global_load_dwordx2 v[94:95], v6, s[74:75]
	v_add_u32_e32 v6, v6, v8
	global_load_dwordx2 v[96:97], v6, s[74:75]
	v_add_u32_e32 v6, v6, v8
	global_load_dwordx2 v[98:99], v6, s[74:75]
	v_add_u32_e32 v6, v6, v8
	global_load_dwordx2 v[100:101], v6, s[74:75]
	v_add_u32_e32 v6, v6, v8
	global_load_dwordx2 v[102:103], v6, s[74:75]
	v_add_u32_e32 v6, v6, v8
	global_load_dwordx2 v[104:105], v6, s[74:75]
	v_add_u32_e32 v6, v6, v8
	global_load_dwordx2 v[106:107], v6, s[74:75]
	v_add_u32_e32 v6, v6, v8
	global_load_dwordx2 v[108:109], v6, s[74:75]
	v_add_u32_e32 v6, v6, v8
	s_waitcnt vmcnt(32)
	s_bitcmp1_b32 s28, 1
	s_cbranch_scc0 .Lcs_64
	global_store_dword v7, v13, s[4:5]
.Lcs_64:
	v_add_u32_e32 v7, v7, v10
	v_fma_f32 v13, v14, v13, v15
	s_bitcmp1_b32 s28, 1
	s_cbranch_scc0 .Lcs_65
	global_store_dword v7, v13, s[4:5]

; __device__ __forceinline__ void carry_phase(const Args& a, int bx) {
;     ...
;         for (int i = 0; i < 32; ++i) { const int j = j0 + i, cj = dir == 0 ? j : NCH - 1 - j; v[i] = tot[(size_t)((b * NCH + cj) * 2 + dir) * LW + c]; }
; #pragma unroll
;         for (int i = 0; i < 32; ++i) { const int j = j0 + i, cj = dir == 0 ? j : NCH - 1 - j; car[(size_t)((b * NCH + cj) * 2 + dir) * LW + c] = hc; hc = v[i].x * hc + v[i].y; }
.Lcs_67:
	v_add_u32_e32 v7, v7, v10
	v_fma_f32 v13, v20, v13, v21
	s_bitcmp1_b32 s28, 1
	s_cbranch_scc0 .Lcs_68
	global_store_dword v7, v13, s[4:5]
.Lcs_68:
	v_add_u32_e32 v7, v7, v10
	v_fma_f32 v13, v22, v13, v23
	s_bitcmp1_b32 s28, 1
	s_cbranch_scc0 .Lcs_69
	global_store_dword v7, v13, s[4:5]
.Lcs_69:
	v_add_u32_e32 v7, v7, v10
	v_fma_f32 v13, v24, v13, v25
	s_bitcmp1_b32 s28, 1
	s_cbranch_scc0 .Lcs_70
	global_store_dword v7, v13, s[4:5]
.Lcs_70:
	v_add_u32_e32 v7, v7, v10
	v_fma_f32 v13, v26, v13, v27
	s_bitcmp1_b32 s28, 1
	s_cbranch_scc0 .Lcs_71
	global_store_dword v7, v13, s[4:5]
.Lcs_71:
	v_add_u32_e32 v7, v7, v10
	v_fma_f32 v13, v28, v13, v29
	s_bitcmp1_b32 s28, 1
	s_cbranch_scc0 .Lcs_72
	global_store_dword v7, v13, s[4:5]
.Lcs_72:
	v_add_u32_e32 v7, v7, v10
	v_fma_f32 v13, v30, v13, v31
	s_bitcmp1_b32 s28, 1
	s_cbranch_scc0 .Lcs_73
	global_store_dword v7, v13, s[4:5]
.Lcs_73:
	v_add_u32_e32 v7, v7, v10
	v_fma_f32 v13, v32, v13, v33
	s_bitcmp1_b32 s28, 1
	s_cbranch_scc0 .Lcs_74
	global_store_dword v7, v13, s[4:5]
.Lcs_74:
	v_add_u32_e32 v7, v7, v10
	v_fma_f32 v13, v34, v13, v35
	s_bitcmp1_b32 s28, 1
	s_cbranch_scc0 .Lcs_75
	global_store_dword v7, v13, s[4:5]
.Lcs_75:
	v_add_u32_e32 v7, v7, v10
	v_fma_f32 v13, v36, v13, v37
	s_bitcmp1_b32 s28, 1
	s_cbranch_scc0 .Lcs_76
	global_store_dword v7, v13, s[4:5]
.Lcs_76:
	v_add_u32_e32 v7, v7, v10
	v_fma_f32 v13, v38, v13, v39
	s_bitcmp1_b32 s28, 1
	s_cbranch_scc0 .Lcs_77
	global_store_dword v7, v13, s[4:5]
.Lcs_77:
	v_add_u32_e32 v7, v7, v10
	v_fma_f32 v13, v40, v13, v41
	s_bitcmp1_b32 s28, 1
	s_cbranch_scc0 .Lcs_78
	global_store_dword v7, v13, s[4:5]
.Lcs_78:
	v_add_u32_e32 v7, v7, v10
	v_fma_f32 v13, v42, v13, v43
	s_bitcmp1_b32 s28, 1
	s_cbranch_scc0 .Lcs_79
	global_store_dword v7, v13, s[4:5]
.Lcs_79:
	v_add_u32_e32 v7, v7, v10
	v_fma_f32 v13, v44, v13, v45
	global_load_dwordx2 v[110:111], v6, s[74:75]
	v_add_u32_e32 v6, v6, v8
	global_load_dwordx2 v[112:113], v6, s[74:75]
	v_add_u32_e32 v6, v6, v8
	global_load_dwordx2 v[114:115], v6, s[74:75]
	v_add_u32_e32 v6, v6, v8
	global_load_dwordx2 v[116:117], v6, s[74:75]
	v_add_u32_e32 v6, v6, v8
	global_load_dwordx2 v[118:119], v6, s[74:75]
	v_add_u32_e32 v6, v6, v8
	global_load_dwordx2 v[120:121], v6, s[74:75]
	v_add_u32_e32 v6, v6, v8
	global_load_dwordx2 v[122:123], v6, s[74:75]
	v_add_u32_e32 v6, v6, v8
	global_load_dwordx2 v[124:125], v6, s[74:75]
	v_add_u32_e32 v6, v6, v8
	global_load_dwordx2 v[126:127], v6, s[74:75]
	v_add_u32_e32 v6, v6, v8
	global_load_dwordx2 v[128:129], v6, s[74:75]
	v_add_u32_e32 v6, v6, v8
	global_load_dwordx2 v[130:131], v6, s[74:75]
	v_add_u32_e32 v6, v6, v8
	global_load_dwordx2 v[132:133], v6, s[74:75]
	v_add_u32_e32 v6, v6, v8
	global_load_dwordx2 v[134:135], v6, s[74:75]
	v_add_u32_e32 v6, v6, v8
	global_load_dwordx2 v[136:137], v6, s[74:75]
	v_add_u32_e32 v6, v6, v8
	global_load_dwordx2 v[138:139], v6, s[74:75]
	v_add_u32_e32 v6, v6, v8
	global_load_dwordx2 v[140:141], v6, s[74:75]
	v_add_u32_e32 v6, v6, v8
	s_waitcnt vmcnt(32)
	s_bitcmp1_b32 s28, 1
	s_cbranch_scc0 .Lcs_80
	global_store_dword v7, v13, s[4:5]
.Lcs_80:
	v_add_u32_e32 v7, v7, v10
	v_fma_f32 v13, v46, v13, v47
	s_bitcmp1_b32 s28, 1
	s_cbranch_scc0 .Lcs_81
	global_store_dword v7, v13, s[4:5]

; __device__ __forceinline__ void carry_phase(const Args& a, int bx) {
;     ...
;         for (int i = 0; i < 32; ++i) { const int j = j0 + i, cj = dir == 0 ? j : NCH - 1 - j; v[i] = tot[(size_t)((b * NCH + cj) * 2 + dir) * LW + c]; }
; #pragma unroll
;         for (int i = 0; i < 32; ++i) { const int j = j0 + i, cj = dir == 0 ? j : NCH - 1 - j; car[(size_t)((b * NCH + cj) * 2 + dir) * LW + c] = hc; hc = v[i].x * hc + v[i].y; }
.Lcs_83:
	v_add_u32_e32 v7, v7, v10
	v_fma_f32 v13, v52, v13, v53
	s_bitcmp1_b32 s28, 1
	s_cbranch_scc0 .Lcs_84
	global_store_dword v7, v13, s[4:5]
.Lcs_84:
	v_add_u32_e32 v7, v7, v10
	v_fma_f32 v13, v54, v13, v55
	s_bitcmp1_b32 s28, 1
	s_cbranch_scc0 .Lcs_85
	global_store_dword v7, v13, s[4:5]
.Lcs_85:
	v_add_u32_e32 v7, v7, v10
	v_fma_f32 v13, v56, v13, v57
	s_bitcmp1_b32 s28, 1
	s_cbranch_scc0 .Lcs_86
	global_store_dword v7, v13, s[4:5]
.Lcs_86:
	v_add_u32_e32 v7, v7, v10
	v_fma_f32 v13, v58, v13, v59
	s_bitcmp1_b32 s28, 1
	s_cbranch_scc0 .Lcs_87
	global_store_dword v7, v13, s[4:5]
.Lcs_87:
	v_add_u32_e32 v7, v7, v10
	v_fma_f32 v13, v60, v13, v61
	s_bitcmp1_b32 s28, 1
	s_cbranch_scc0 .Lcs_88
	global_store_dword v7, v13, s[4:5]
.Lcs_88:
	v_add_u32_e32 v7, v7, v10
	v_fma_f32 v13, v62, v13, v63
	s_bitcmp1_b32 s28, 1
	s_cbranch_scc0 .Lcs_89
	global_store_dword v7, v13, s[4:5]
.Lcs_89:
	v_add_u32_e32 v7, v7, v10
	v_fma_f32 v13, v64, v13, v65
	s_bitcmp1_b32 s28, 1
	s_cbranch_scc0 .Lcs_90
	global_store_dword v7, v13, s[4:5]
.Lcs_90:
	v_add_u32_e32 v7, v7, v10
	v_fma_f32 v13, v66, v13, v67
	s_bitcmp1_b32 s28, 1
	s_cbranch_scc0 .Lcs_91
	global_store_dword v7, v13, s[4:5]
.Lcs_91:
	v_add_u32_e32 v7, v7, v10
	v_fma_f32 v13, v68, v13, v69
	s_bitcmp1_b32 s28, 1
	s_cbranch_scc0 .Lcs_92
	global_store_dword v7, v13, s[4:5]
.Lcs_92:
	v_add_u32_e32 v7, v7, v10
	v_fma_f32 v13, v70, v13, v71
	s_bitcmp1_b32 s28, 1
	s_cbranch_scc0 .Lcs_93
	global_store_dword v7, v13, s[4:5]
.Lcs_93:
	v_add_u32_e32 v7, v7, v10
	v_fma_f32 v13, v72, v13, v73
	s_bitcmp1_b32 s28, 1
	s_cbranch_scc0 .Lcs_94
	global_store_dword v7, v13, s[4:5]
.Lcs_94:
	v_add_u32_e32 v7, v7, v10
	v_fma_f32 v13, v74, v13, v75
	s_bitcmp1_b32 s28, 1
	s_cbranch_scc0 .Lcs_95
	global_store_dword v7, v13, s[4:5]
.Lcs_95:
	v_add_u32_e32 v7, v7, v10
	v_fma_f32 v13, v76, v13, v77
	s_waitcnt vmcnt(16)
	s_bitcmp1_b32 s28, 1
	s_cbranch_scc0 .Lcs_96
	global_store_dword v7, v13, s[4:5]
.Lcs_96:
	v_add_u32_e32 v7, v7, v10
	v_fma_f32 v13, v78, v13, v79
	s_bitcmp1_b32 s28, 1
	s_cbranch_scc0 .Lcs_97
	global_store_dword v7, v13, s[4:5]

; __device__ __forceinline__ void carry_phase(const Args& a, int bx) {
;     ...
;         for (int i = 0; i < 32; ++i) { const int j = j0 + i, cj = dir == 0 ? j : NCH - 1 - j; v[i] = tot[(size_t)((b * NCH + cj) * 2 + dir) * LW + c]; }
; #pragma unroll
;         for (int i = 0; i < 32; ++i) { const int j = j0 + i, cj = dir == 0 ? j : NCH - 1 - j; car[(size_t)((b * NCH + cj) * 2 + dir) * LW + c] = hc; hc = v[i].x * hc + v[i].y; }
.Lcs_99:
	v_add_u32_e32 v7, v7, v10
	v_fma_f32 v13, v84, v13, v85
	s_bitcmp1_b32 s28, 1
	s_cbranch_scc0 .Lcs_100
	global_store_dword v7, v13, s[4:5]
.Lcs_100:
	v_add_u32_e32 v7, v7, v10
	v_fma_f32 v13, v86, v13, v87
	s_bitcmp1_b32 s28, 1
	s_cbranch_scc0 .Lcs_101
	global_store_dword v7, v13, s[4:5]
.Lcs_101:
	v_add_u32_e32 v7, v7, v10
	v_fma_f32 v13, v88, v13, v89
	s_bitcmp1_b32 s28, 1
	s_cbranch_scc0 .Lcs_102
	global_store_dword v7, v13, s[4:5]
.Lcs_102:
	v_add_u32_e32 v7, v7, v10
	v_fma_f32 v13, v90, v13, v91
	s_bitcmp1_b32 s28, 1
	s_cbranch_scc0 .Lcs_103
	global_store_dword v7, v13, s[4:5]
.Lcs_103:
	v_add_u32_e32 v7, v7, v10
	v_fma_f32 v13, v92, v13, v93
	s_bitcmp1_b32 s28, 1
	s_cbranch_scc0 .Lcs_104
	global_store_dword v7, v13, s[4:5]
.Lcs_104:
	v_add_u32_e32 v7, v7, v10
	v_fma_f32 v13, v94, v13, v95
	s_bitcmp1_b32 s28, 1
	s_cbranch_scc0 .Lcs_105
	global_store_dword v7, v13, s[4:5]
.Lcs_105:
	v_add_u32_e32 v7, v7, v10
	v_fma_f32 v13, v96, v13, v97
	s_bitcmp1_b32 s28, 1
	s_cbranch_scc0 .Lcs_106
	global_store_dword v7, v13, s[4:5]
.Lcs_106:
	v_add_u32_e32 v7, v7, v10
	v_fma_f32 v13, v98, v13, v99
	s_bitcmp1_b32 s28, 1
	s_cbranch_scc0 .Lcs_107
	global_store_dword v7, v13, s[4:5]
.Lcs_107:
	v_add_u32_e32 v7, v7, v10
	v_fma_f32 v13, v100, v13, v101
	s_bitcmp1_b32 s28, 1
	s_cbranch_scc0 .Lcs_108
	global_store_dword v7, v13, s[4:5]
.Lcs_108:
	v_add_u32_e32 v7, v7, v10
	v_fma_f32 v13, v102, v13, v103
	s_bitcmp1_b32 s28, 1
	s_cbranch_scc0 .Lcs_109
	global_store_dword v7, v13, s[4:5]
.Lcs_109:
	v_add_u32_e32 v7, v7, v10
	v_fma_f32 v13, v104, v13, v105
	s_bitcmp1_b32 s28, 1
	s_cbranch_scc0 .Lcs_110
	global_store_dword v7, v13, s[4:5]
.Lcs_110:
	v_add_u32_e32 v7, v7, v10
	v_fma_f32 v13, v106, v13, v107
	s_bitcmp1_b32 s28, 1
	s_cbranch_scc0 .Lcs_111
	global_store_dword v7, v13, s[4:5]
.Lcs_111:
	v_add_u32_e32 v7, v7, v10
	v_fma_f32 v13, v108, v13, v109
	s_waitcnt vmcnt(0)
	s_bitcmp1_b32 s28, 1
	s_cbranch_scc0 .Lcs_112
	global_store_dword v7, v13, s[4:5]
.Lcs_112:
	v_add_u32_e32 v7, v7, v10
	v_fma_f32 v13, v110, v13, v111
	s_bitcmp1_b32 s28, 1
	s_cbranch_scc0 .Lcs_113
	global_store_dword v7, v13, s[4:5]

; __device__ __forceinline__ void carry_phase(const Args& a, int bx) {
;     ...
;         for (int i = 0; i < 32; ++i) { const int j = j0 + i, cj = dir == 0 ? j : NCH - 1 - j; v[i] = tot[(size_t)((b * NCH + cj) * 2 + dir) * LW + c]; }
; #pragma unroll
;         for (int i = 0; i < 32; ++i) { const int j = j0 + i, cj = dir == 0 ? j : NCH - 1 - j; car[(size_t)((b * NCH + cj) * 2 + dir) * LW + c] = hc; hc = v[i].x * hc + v[i].y; }
.Lcs_115:
	v_add_u32_e32 v7, v7, v10
	v_fma_f32 v13, v116, v13, v117
	s_bitcmp1_b32 s28, 1
	s_cbranch_scc0 .Lcs_116
	global_store_dword v7, v13, s[4:5]
.Lcs_116:
	v_add_u32_e32 v7, v7, v10
	v_fma_f32 v13, v118, v13, v119
	s_bitcmp1_b32 s28, 1
	s_cbranch_scc0 .Lcs_117
	global_store_dword v7, v13, s[4:5]
.Lcs_117:
	v_add_u32_e32 v7, v7, v10
	v_fma_f32 v13, v120, v13, v121
	s_bitcmp1_b32 s28, 1
	s_cbranch_scc0 .Lcs_118
	global_store_dword v7, v13, s[4:5]
.Lcs_118:
	v_add_u32_e32 v7, v7, v10
	v_fma_f32 v13, v122, v13, v123
	s_bitcmp1_b32 s28, 1
	s_cbranch_scc0 .Lcs_119
	global_store_dword v7, v13, s[4:5]
.Lcs_119:
	v_add_u32_e32 v7, v7, v10
	v_fma_f32 v13, v124, v13, v125
	s_bitcmp1_b32 s28, 1
	s_cbranch_scc0 .Lcs_120
	global_store_dword v7, v13, s[4:5]
.Lcs_120:
	v_add_u32_e32 v7, v7, v10
	v_fma_f32 v13, v126, v13, v127
	s_bitcmp1_b32 s28, 1
	s_cbranch_scc0 .Lcs_121
	global_store_dword v7, v13, s[4:5]
.Lcs_121:
	v_add_u32_e32 v7, v7, v10
	v_fma_f32 v13, v128, v13, v129
	s_bitcmp1_b32 s28, 1
	s_cbranch_scc0 .Lcs_122
	global_store_dword v7, v13, s[4:5]
.Lcs_122:
	v_add_u32_e32 v7, v7, v10
	v_fma_f32 v13, v130, v13, v131
	s_bitcmp1_b32 s28, 1
	s_cbranch_scc0 .Lcs_123
	global_store_dword v7, v13, s[4:5]
.Lcs_123:
	v_add_u32_e32 v7, v7, v10
	v_fma_f32 v13, v132, v13, v133
	s_bitcmp1_b32 s28, 1
	s_cbranch_scc0 .Lcs_124
	global_store_dword v7, v13, s[4:5]
.Lcs_124:
	v_add_u32_e32 v7, v7, v10
	v_fma_f32 v13, v134, v13, v135
	s_bitcmp1_b32 s28, 1
	s_cbranch_scc0 .Lcs_125
	global_store_dword v7, v13, s[4:5]
.Lcs_125:
	v_add_u32_e32 v7, v7, v10
	v_fma_f32 v13, v136, v13, v137
	s_bitcmp1_b32 s28, 1
	s_cbranch_scc0 .Lcs_126
	global_store_dword v7, v13, s[4:5]
.Lcs_126:
	v_add_u32_e32 v7, v7, v10
	v_fma_f32 v13, v138, v13, v139
	s_bitcmp1_b32 s28, 1
	s_cbranch_scc0 .Lcs_127
	global_store_dword v7, v13, s[4:5]

; #define LAS __attribute__((address_space(3)))
; __device__ __forceinline__ void lru_finish3(const Args& a, int l, int bx, int G, LAS unsigned char* lds) {
;     int tid_ = threadIdx.x; asm volatile("" : "+v"(tid_));
;     const int tid = tid_, lane = tid & 63, wave = __builtin_amdgcn_readfirstlane(tid >> 6);
;     const bf16* proj = (const bf16*)(a.ws + WS_PROJ); const unsigned* HP = (const unsigned*)(a.ws + WS_HP);
;     bf16* Y = (bf16*)(a.ws + WS_Y);
;     const float* gn = a.in[16] + l * LW + lane * 8;
;     const f32x4 gn0 = *(const f32x4*)gn, gn1 = *(const f32x4*)(gn + 4);
; #pragma unroll 1
;     for (int p = bx; p < NB * NCH / 2; p += G) {
;         const int b = p / (NCH / 2), ch0 = 2 * (p % (NCH / 2)), ch1 = ch0 + 1;
;         const int kw = wave >> 2;
;         const float* cfp = (const float*)(a.ws + WS_CAR) + (size_t)((b * NCH + ch0 + kw) * 2) * LW + lane * 8;
;         const f32x4 cf0 = *(const f32x4*)cfp, cf1 = *(const f32x4*)(cfp + 4), cb0 = *(const f32x4*)(cfp + LW), cb1 = *(const f32x4*)(cfp + LW + 4);
.LBB0_307:
	s_or_b64 exec, exec, s[0:1]
	v_readlane_b32 s0, v253, 37
	v_mov_b32_e32 v0, v226
	v_readlane_b32 s1, v253, 38
	s_waitcnt lgkmcnt(0)
	s_barrier
	s_andn2_b64 vcc, exec, s[0:1]
	v_readfirstlane_b32 s0, v0
	s_cbranch_vccnz .LBB0_313
	v_lshlrev_b32_e32 v0, 3, v0
	v_and_b32_e32 v10, 0x1f8, v0
	v_readlane_b32 s4, v254, 47
	v_lshlrev_b32_e32 v0, 2, v10
	v_readlane_b32 s5, v254, 48
	s_nop 4
	global_load_dwordx4 v[2:5], v0, s[4:5]
	global_load_dwordx4 v[6:9], v0, s[4:5] offset:16
	s_ashr_i32 s1, s0, 3
	s_ashr_i32 s0, s0, 7
	s_and_b32 s28, s1, -8
	s_and_b32 s29, s0, -2
	v_readlane_b32 s0, v253, 35
	v_readlane_b32 s1, v253, 36
	v_lshl_add_u64 v[104:105], s[72:73], 0, v[0:1]
	s_and_b32 s46, s2, 7
	s_lshl_b32 s46, s46, 5
	s_lshr_b32 s38, s2, 3
	s_or_b32 s46, s46, s38
	v_lshl_add_u64 v[102:103], s[0:1], 0, v[0:1]
	v_readlane_b32 s0, v254, 10
	v_lshlrev_b32_e32 v0, 1, v10
	v_readlane_b32 s1, v254, 11
	s_waitcnt vmcnt(1)
	v_mov_b32_e32 v108, v3
	v_lshl_add_u64 v[106:107], s[0:1], 0, v[0:1]
	v_lshlrev_b32_e32 v0, 1, v10
	v_mov_b32_e32 v109, v5
	v_mov_b32_e32 v3, v4
	s_waitcnt vmcnt(0)
	v_mov_b32_e32 v4, v7
	v_mov_b32_e32 v5, v9
	v_mov_b32_e32 v7, v8
